# P2 order swap selected per XCD (alternate XCDs run mixers first) instead of per group of 8 workgroups
# baseline (speedup 1.0000x reference)
.LBB0_389:
	s_andn2_b64 vcc, exec, s[26:27]
	s_cbranch_vccnz .LBB0_525
	v_readlane_b32 s98, v241, 45
	s_nop 1
	s_bfe_u32 s98, s98, 0x10005

.LBB0_393:
	v_mov_b32_e32 v153, v224
	s_and_b32 s16, s13, 7
	s_xor_b32 s70, s16, 15
	v_readfirstlane_b32 s25, v153
	s_ashr_i32 s62, s25, 6
	s_lshl_b32 s25, s70, 7
	s_lshl_b32 s30, s62, 4
	s_ashr_i32 s38, s13, 5
	v_and_b32_e32 v2, 15, v153
	s_add_i32 s30, s30, s25
	s_ashr_i32 s39, s38, 31
	v_or_b32_e32 v4, s30, v2
	s_lshl_b64 s[44:45], s[38:39], 11
	v_ashrrev_i32_e32 v5, 31, v4
	v_lshl_add_u64 v[136:137], s[44:45], 0, v[4:5]
	v_mov_b64_e32 v[4:5], s[28:29]
	s_lshl_b32 s25, s13, 4
	v_mad_u64_u32 v[4:5], s[46:47], v136, s23, v[4:5]
	s_and_b32 s39, s25, 0x180
	v_mad_i32_i24 v5, v137, s23, v5
	s_lshl_b32 s30, s39, 1
	v_lshl_add_u64 v[138:139], v[4:5], 0, s[30:31]
	v_and_b32_e32 v0, 48, v153
	v_lshl_add_u64 v[4:5], v[138:139], 0, v[0:1]
	global_load_dwordx4 v[28:31], v[4:5], off
	global_load_dwordx4 v[32:35], v[4:5], off offset:64
	global_load_dwordx4 v[36:39], v[4:5], off offset:128
	global_load_dwordx4 v[40:43], v[4:5], off offset:192
	s_cmp_lt_i32 s62, 4
	s_cbranch_scc1 .LBB0_395
	s_setprio 0

.LBB0_417:
	s_setprio 0
	ds_bpermute_b32 v0, v148, v162
	s_waitcnt lgkmcnt(0)
	v_add_f32_e32 v0, v162, v0
	ds_bpermute_b32 v2, v149, v0
	s_waitcnt lgkmcnt(0)
	v_add_f32_e32 v0, v0, v2
	ds_bpermute_b32 v2, v148, v160
	s_waitcnt lgkmcnt(0)
	v_add_f32_e32 v2, v160, v2
	ds_bpermute_b32 v3, v149, v2
	s_waitcnt lgkmcnt(0)
	v_add_f32_e32 v2, v2, v3
	v_div_scale_f32 v3, s[38:39], v0, v0, 1.0
	v_rcp_f32_e32 v28, v3
	s_nop 0
	v_fma_f32 v29, -v3, v28, 1.0
	v_fmac_f32_e32 v28, v29, v28
	v_div_scale_f32 v29, vcc, 1.0, v0, 1.0
	v_mul_f32_e32 v30, v29, v28
	v_fma_f32 v31, -v3, v30, v29
	v_fmac_f32_e32 v30, v31, v28
	v_fma_f32 v3, -v3, v30, v29
	v_div_fmas_f32 v3, v3, v28, v30
	v_div_fixup_f32 v0, v3, v0, 1.0
	v_div_scale_f32 v3, s[38:39], v2, v2, v150
	v_rcp_f32_e32 v28, v3
	s_nop 0
	v_fma_f32 v29, -v3, v28, 1.0
	v_fmac_f32_e32 v28, v29, v28
	v_div_scale_f32 v29, vcc, v150, v2, v150
	v_mul_f32_e32 v30, v29, v28
	v_fma_f32 v31, -v3, v30, v29
	v_fmac_f32_e32 v30, v31, v28
	v_fma_f32 v3, -v3, v30, v29
	v_div_fmas_f32 v3, v3, v28, v30
	v_div_fixup_f32 v2, v3, v2, v150
	v_pk_mul_f32 v[28:29], v[80:81], v[2:3] op_sel_hi:[1,0]
	v_pk_mul_f32 v[30:31], v[82:83], v[2:3] op_sel_hi:[1,0]
	v_pk_fma_f32 v[38:39], v[72:73], v[0:1], v[28:29] op_sel_hi:[1,0,1] neg_lo:[0,0,1] neg_hi:[0,0,1]
	v_pk_mul_f32 v[28:29], v[76:77], v[2:3] op_sel_hi:[1,0]
	v_pk_fma_f32 v[36:37], v[74:75], v[0:1], v[30:31] op_sel_hi:[1,0,1] neg_lo:[0,0,1] neg_hi:[0,0,1]
	v_pk_mul_f32 v[30:31], v[78:79], v[2:3] op_sel_hi:[1,0]
	v_pk_fma_f32 v[42:43], v[68:69], v[0:1], v[28:29] op_sel_hi:[1,0,1] neg_lo:[0,0,1] neg_hi:[0,0,1]
	v_pk_fma_f32 v[40:41], v[70:71], v[0:1], v[30:31] op_sel_hi:[1,0,1] neg_lo:[0,0,1] neg_hi:[0,0,1]
	v_mov_b32_e32 v30, v39
	v_mov_b32_e32 v31, v43
	v_mov_b32_e32 v28, v38
	v_mov_b32_e32 v29, v42
	v_pk_mul_f32 v[30:31], v[30:31], v[30:31]
	v_mov_b32_e32 v32, v37
	v_mov_b32_e32 v33, v41
	v_pk_fma_f32 v[28:29], v[28:29], v[28:29], v[30:31]
	v_mov_b32_e32 v30, v36
	v_mov_b32_e32 v31, v40
	v_pk_mul_f32 v[32:33], v[32:33], v[32:33]
	v_pk_mul_f32 v[44:45], v[44:45], v[2:3] op_sel_hi:[1,0]
	v_pk_fma_f32 v[30:31], v[30:31], v[30:31], v[32:33]
	v_pk_mul_f32 v[46:47], v[46:47], v[2:3] op_sel_hi:[1,0]
	v_pk_add_f32 v[28:29], v[28:29], v[30:31]
	v_pk_mul_f32 v[30:31], v[66:67], v[2:3] op_sel_hi:[1,0]
	v_pk_add_f32 v[68:69], v[28:29], v[28:29] op_sel_hi:[0,1]
	v_pk_mul_f32 v[28:29], v[64:65], v[2:3] op_sel_hi:[1,0]
	v_pk_fma_f32 v[30:31], v[62:63], v[0:1], v[30:31] op_sel_hi:[1,0,1] neg_lo:[0,0,1] neg_hi:[0,0,1]
	v_pk_fma_f32 v[28:29], v[60:61], v[0:1], v[28:29] op_sel_hi:[1,0,1] neg_lo:[0,0,1] neg_hi:[0,0,1]
	v_pk_mul_f32 v[32:33], v[30:31], v[30:31]
	v_pk_mul_f32 v[34:35], v[28:29], v[28:29]
	v_pk_fma_f32 v[26:27], v[26:27], v[0:1], v[46:47] op_sel_hi:[1,0,1] neg_lo:[0,0,1] neg_hi:[0,0,1]
	v_pk_mov_b32 v[60:61], v[34:35], v[32:33] op_sel:[1,0]
	v_mov_b32_e32 v35, v33
	v_pk_add_f32 v[32:33], v[60:61], v[34:35]
	v_pk_mul_f32 v[34:35], v[56:57], v[2:3] op_sel_hi:[1,0]
	v_pk_add_f32 v[60:61], v[32:33], v[32:33] op_sel_hi:[0,1]
	v_pk_fma_f32 v[34:35], v[48:49], v[0:1], v[34:35] op_sel_hi:[1,0,1] neg_lo:[0,0,1] neg_hi:[0,0,1]
	v_pk_mul_f32 v[32:33], v[58:59], v[2:3] op_sel_hi:[1,0]
	v_mul_f32_e32 v48, v34, v34
	v_pk_fma_f32 v[32:33], v[50:51], v[0:1], v[32:33] op_sel_hi:[1,0,1] neg_lo:[0,0,1] neg_hi:[0,0,1]
	v_pk_fma_f32 v[48:49], v[34:35], v[34:35], v[48:49] op_sel_hi:[1,1,0]
	v_pk_fma_f32 v[24:25], v[24:25], v[0:1], v[44:45] op_sel_hi:[1,0,1] neg_lo:[0,0,1] neg_hi:[0,0,1]
	v_mul_f32_e32 v48, v32, v32
	v_pk_fma_f32 v[50:51], v[32:33], v[32:33], v[48:49] op_sel_hi:[1,1,0]
	v_pk_mul_f32 v[22:23], v[22:23], v[2:3] op_sel_hi:[1,0]
	v_pk_mul_f32 v[20:21], v[20:21], v[2:3] op_sel_hi:[1,0]
	v_pk_mul_f32 v[12:13], v[12:13], v[2:3] op_sel_hi:[1,0]
	v_mul_f32_e32 v48, v24, v24
	v_mul_f32_e32 v50, v25, v25
	v_mul_f32_e32 v60, v26, v26
	v_mul_f32_e32 v68, v27, v27
	v_pk_fma_f32 v[16:17], v[16:17], v[0:1], v[20:21] op_sel_hi:[1,0,1] neg_lo:[0,0,1] neg_hi:[0,0,1]
	v_pk_fma_f32 v[20:21], v[18:19], v[0:1], v[22:23] op_sel_hi:[1,0,1] neg_lo:[0,0,1] neg_hi:[0,0,1]
	v_pk_mul_f32 v[14:15], v[14:15], v[2:3] op_sel_hi:[1,0]
	v_pk_fma_f32 v[8:9], v[8:9], v[0:1], v[12:13] op_sel_hi:[1,0,1] neg_lo:[0,0,1] neg_hi:[0,0,1]
	v_pk_add_f32 v[44:45], v[48:49], v[50:51]
	v_pk_add_f32 v[46:47], v[60:61], v[68:69]
	v_pk_mul_f32 v[18:19], v[20:21], v[20:21]
	v_pk_mul_f32 v[22:23], v[16:17], v[16:17]
	v_pk_fma_f32 v[10:11], v[10:11], v[0:1], v[14:15] op_sel_hi:[1,0,1] neg_lo:[0,0,1] neg_hi:[0,0,1]
	v_mul_f32_e32 v12, v8, v8
	v_pk_add_f32 v[44:45], v[44:45], v[46:47]
	v_pk_mov_b32 v[46:47], v[22:23], v[18:19] op_sel:[1,0]
	v_mov_b32_e32 v23, v19
	v_pk_fma_f32 v[14:15], v[8:9], v[8:9], v[12:13] op_sel_hi:[1,1,0]
	v_mul_f32_e32 v12, v10, v10
	v_pk_add_f32 v[18:19], v[46:47], v[22:23]
	v_pk_fma_f32 v[22:23], v[10:11], v[10:11], v[12:13] op_sel_hi:[1,1,0]
	v_pk_mul_f32 v[12:13], v[52:53], v[2:3] op_sel_hi:[1,0]
	v_pk_mul_f32 v[2:3], v[54:55], v[2:3] op_sel_hi:[1,0]
	v_pk_add_f32 v[44:45], v[44:45], v[44:45] op_sel_hi:[0,1]
	v_pk_add_f32 v[18:19], v[18:19], v[18:19] op_sel_hi:[0,1]
	v_pk_fma_f32 v[6:7], v[6:7], v[0:1], v[2:3] op_sel_hi:[1,0,1] neg_lo:[0,0,1] neg_hi:[0,0,1]
	v_pk_fma_f32 v[12:13], v[4:5], v[0:1], v[12:13] op_sel_hi:[1,0,1] neg_lo:[0,0,1] neg_hi:[0,0,1]
	v_mul_f32_e32 v18, v6, v6
	v_mul_f32_e32 v14, v12, v12
	v_mul_f32_e32 v22, v13, v13
	v_mul_f32_e32 v44, v7, v7
	v_pk_add_f32 v[2:3], v[14:15], v[22:23]
	v_pk_add_f32 v[4:5], v[18:19], v[44:45]
	s_nop 0
	v_pk_add_f32 v[2:3], v[2:3], v[4:5]
	s_nop 0
	v_add_f32_e32 v0, v2, v3
	ds_bpermute_b32 v2, v148, v0
	s_waitcnt lgkmcnt(0)
	v_add_f32_e32 v0, v0, v2
	ds_bpermute_b32 v2, v149, v0
	s_waitcnt lgkmcnt(0)
	v_add_f32_e32 v0, v0, v2
	v_fmamk_f32 v0, v0, 0x3c000000, v227
	v_cmp_gt_f32_e32 vcc, s7, v0
	v_mul_f32_e32 v2, 0x4f800000, v0
	s_nop 0
	v_cndmask_b32_e32 v0, v0, v2, vcc
	v_sqrt_f32_e32 v2, v0
	s_nop 0
	v_add_u32_e32 v3, -1, v2
	v_fma_f32 v4, -v3, v2, v0
	v_cmp_ge_f32_e64 s[38:39], 0, v4
	v_add_u32_e32 v4, 1, v2
	s_nop 0
	v_cndmask_b32_e64 v3, v2, v3, s[38:39]
	v_fma_f32 v2, -v4, v2, v0
	v_cmp_lt_f32_e64 s[38:39], 0, v2
	s_nop 1
	v_cndmask_b32_e64 v2, v3, v4, s[38:39]
	v_mul_f32_e32 v3, 0x37800000, v2
	v_cndmask_b32_e32 v2, v2, v3, vcc
	v_cmp_class_f32_e32 vcc, v0, v228
	s_nop 1
	v_cndmask_b32_e32 v0, v2, v0, vcc
	v_div_scale_f32 v2, s[38:39], v0, v0, v151
	v_rcp_f32_e32 v3, v2
	s_nop 0
	v_fma_f32 v4, -v2, v3, 1.0
	v_fmac_f32_e32 v3, v4, v3
	v_div_scale_f32 v4, vcc, v151, v0, v151
	v_mul_f32_e32 v5, v4, v3
	v_fma_f32 v14, -v2, v5, v4
	v_fmac_f32_e32 v5, v14, v3
	v_fma_f32 v2, -v2, v5, v4
	v_div_fmas_f32 v2, v2, v3, v5
	v_div_fixup_f32 v18, v2, v0, v151
	v_and_b32_e32 v0, 16, v153
	v_lshrrev_b32_e32 v2, 2, v153
	v_and_or_b32 v0, v2, 8, v0
	v_mov_b64_e32 v[2:3], s[50:51]
	v_mad_u64_u32 v[2:3], s[38:39], v136, s21, v[2:3]
	v_mad_i32_i24 v3, v137, s21, v3
	v_lshl_add_u64 v[2:3], v[2:3], 0, s[30:31]
	v_lshlrev_b32_e32 v0, 1, v0
	v_lshl_add_u64 v[22:23], v[2:3], 0, v[0:1]
	v_lshl_add_u64 v[14:15], v[138:139], 0, v[0:1]
	v_lshlrev_b32_e32 v0, 4, v152
	global_load_dwordx4 v[2:5], v[22:23], off offset:1024
	global_load_dwordx4 v[44:47], v0, s[42:43]
	global_load_dwordx4 v[48:51], v0, s[42:43] offset:64
	v_pk_mul_f32 v[38:39], v[38:39], v[18:19] op_sel_hi:[1,0]
	v_pk_mul_f32 v[42:43], v[42:43], v[18:19] op_sel_hi:[1,0]
	v_pk_mul_f32 v[36:37], v[36:37], v[18:19] op_sel_hi:[1,0]
	v_pk_mul_f32 v[40:41], v[40:41], v[18:19] op_sel_hi:[1,0]
	v_mov_b32_e32 v153, v224
	s_lshl_b32 s39, s16, 7
	s_waitcnt vmcnt(0)
	v_lshlrev_b32_e32 v19, 16, v2
	v_pk_mul_f32 v[38:39], v[44:45], v[38:39]
	v_pk_mul_f32 v[42:43], v[48:49], v[42:43]
	v_and_b32_e32 v2, 0xffff0000, v2
	s_nop 0
	v_permlane16_swap_b32_e32 v38, v42
	v_permlane16_swap_b32_e32 v39, v43
	v_pk_mul_f32 v[36:37], v[46:47], v[36:37]
	v_pk_mul_f32 v[40:41], v[50:51], v[40:41]
	v_mul_f32_e32 v19, v19, v38
	v_mul_f32_e32 v2, v2, v39
	v_permlane16_swap_b32_e32 v36, v40
	v_permlane16_swap_b32_e32 v37, v41
	v_cvt_pk_bf16_f32 v2, v19, v2
	v_lshlrev_b32_e32 v19, 16, v3
	v_and_b32_e32 v3, 0xffff0000, v3
	v_mul_f32_e32 v19, v19, v36
	v_mul_f32_e32 v3, v3, v37
	v_cvt_pk_bf16_f32 v3, v19, v3
	v_lshlrev_b32_e32 v19, 16, v4
	v_and_b32_e32 v4, 0xffff0000, v4
	v_mul_f32_e32 v19, v19, v42
	v_mul_f32_e32 v4, v4, v43
	v_cvt_pk_bf16_f32 v4, v19, v4
	v_lshlrev_b32_e32 v19, 16, v5
	v_and_b32_e32 v5, 0xffff0000, v5
	v_mul_f32_e32 v5, v5, v41
	v_mul_f32_e32 v19, v19, v40
	v_cvt_pk_bf16_f32 v5, v19, v5
	global_store_dwordx4 v[14:15], v[2:5], off sc1
	global_load_dwordx4 v[2:5], v[22:23], off offset:1088
	s_nop 0
	global_load_dwordx4 v[36:39], v0, s[42:43] offset:128
	global_load_dwordx4 v[40:43], v0, s[42:43] offset:192
	v_pk_mul_f32 v[28:29], v[28:29], v[18:19] op_sel_hi:[1,0]
	v_pk_mul_f32 v[34:35], v[34:35], v[18:19] op_sel_hi:[1,0]
	v_pk_mul_f32 v[30:31], v[30:31], v[18:19] op_sel_hi:[1,0]
	v_pk_mul_f32 v[32:33], v[32:33], v[18:19] op_sel_hi:[1,0]
	s_waitcnt vmcnt(2)
	v_lshlrev_b32_e32 v19, 16, v2
	s_waitcnt vmcnt(1)
	v_pk_mul_f32 v[28:29], v[36:37], v[28:29]
	s_waitcnt vmcnt(0)
	v_pk_mul_f32 v[34:35], v[40:41], v[34:35]
	v_and_b32_e32 v2, 0xffff0000, v2
	s_nop 0
	v_permlane16_swap_b32_e32 v28, v34
	v_permlane16_swap_b32_e32 v29, v35
	v_pk_mul_f32 v[30:31], v[38:39], v[30:31]
	v_pk_mul_f32 v[32:33], v[42:43], v[32:33]
	v_mul_f32_e32 v19, v19, v28
	v_mul_f32_e32 v2, v2, v29
	v_permlane16_swap_b32_e32 v30, v32
	v_permlane16_swap_b32_e32 v31, v33
	v_cvt_pk_bf16_f32 v2, v19, v2
	v_lshlrev_b32_e32 v19, 16, v3
	v_and_b32_e32 v3, 0xffff0000, v3
	v_mul_f32_e32 v19, v19, v30
	v_mul_f32_e32 v3, v3, v31
	v_cvt_pk_bf16_f32 v3, v19, v3
	v_lshlrev_b32_e32 v19, 16, v4
	v_and_b32_e32 v4, 0xffff0000, v4
	v_mul_f32_e32 v19, v19, v34
	v_mul_f32_e32 v4, v4, v35
	v_cvt_pk_bf16_f32 v4, v19, v4
	v_lshlrev_b32_e32 v19, 16, v5
	v_and_b32_e32 v5, 0xffff0000, v5
	v_mul_f32_e32 v5, v5, v33
	v_mul_f32_e32 v19, v19, v32
	v_cvt_pk_bf16_f32 v5, v19, v5
	global_store_dwordx4 v[14:15], v[2:5], off offset:64 sc1
	global_load_dwordx4 v[2:5], v[22:23], off offset:1152
	s_nop 0
	global_load_dwordx4 v[28:31], v0, s[42:43] offset:256
	global_load_dwordx4 v[32:35], v0, s[42:43] offset:320
	v_pk_mul_f32 v[24:25], v[24:25], v[18:19] op_sel_hi:[1,0]
	v_pk_mul_f32 v[16:17], v[16:17], v[18:19] op_sel_hi:[1,0]
	v_pk_mul_f32 v[26:27], v[26:27], v[18:19] op_sel_hi:[1,0]
	v_pk_mul_f32 v[20:21], v[20:21], v[18:19] op_sel_hi:[1,0]
	s_waitcnt vmcnt(2)
	v_lshlrev_b32_e32 v19, 16, v2
	s_waitcnt vmcnt(1)
	v_pk_mul_f32 v[24:25], v[24:25], v[28:29]
	s_waitcnt vmcnt(0)
	v_pk_mul_f32 v[16:17], v[16:17], v[32:33]
	v_and_b32_e32 v2, 0xffff0000, v2
	s_nop 0
	v_permlane16_swap_b32_e32 v24, v16
	v_permlane16_swap_b32_e32 v25, v17
	v_pk_mul_f32 v[26:27], v[26:27], v[30:31]
	v_pk_mul_f32 v[20:21], v[20:21], v[34:35]
	v_mul_f32_e32 v19, v19, v24
	v_mul_f32_e32 v2, v2, v25
	v_permlane16_swap_b32_e32 v26, v20
	v_permlane16_swap_b32_e32 v27, v21
	v_cvt_pk_bf16_f32 v2, v19, v2
	v_lshlrev_b32_e32 v19, 16, v3
	v_and_b32_e32 v3, 0xffff0000, v3
	v_mul_f32_e32 v19, v19, v26
	v_mul_f32_e32 v3, v3, v27
	v_cvt_pk_bf16_f32 v3, v19, v3
	v_lshlrev_b32_e32 v19, 16, v4
	v_and_b32_e32 v4, 0xffff0000, v4
	v_mul_f32_e32 v16, v19, v16
	v_mul_f32_e32 v4, v4, v17
	v_cvt_pk_bf16_f32 v4, v16, v4
	v_lshlrev_b32_e32 v16, 16, v5
	v_and_b32_e32 v5, 0xffff0000, v5
	v_mul_f32_e32 v5, v5, v21
	v_mul_f32_e32 v16, v16, v20
	v_cvt_pk_bf16_f32 v5, v16, v5
	global_store_dwordx4 v[14:15], v[2:5], off offset:128 sc1
	global_load_dwordx4 v[2:5], v[22:23], off offset:1216
	s_nop 0
	global_load_dwordx4 v[20:23], v0, s[42:43] offset:384
	global_load_dwordx4 v[24:27], v0, s[42:43] offset:448
	v_pk_mul_f32 v[8:9], v[8:9], v[18:19] op_sel_hi:[1,0]
	v_pk_mul_f32 v[12:13], v[12:13], v[18:19] op_sel_hi:[1,0]
	v_pk_mul_f32 v[10:11], v[10:11], v[18:19] op_sel_hi:[1,0]
	v_pk_mul_f32 v[6:7], v[6:7], v[18:19] op_sel_hi:[1,0]
	s_waitcnt vmcnt(2)
	v_lshlrev_b32_e32 v0, 16, v2
	s_waitcnt vmcnt(1)
	v_pk_mul_f32 v[8:9], v[8:9], v[20:21]
	s_waitcnt vmcnt(0)
	v_pk_mul_f32 v[12:13], v[12:13], v[24:25]
	v_and_b32_e32 v2, 0xffff0000, v2
	s_nop 0
	v_permlane16_swap_b32_e32 v8, v12
	v_permlane16_swap_b32_e32 v9, v13
	v_pk_mul_f32 v[10:11], v[10:11], v[22:23]
	v_pk_mul_f32 v[6:7], v[6:7], v[26:27]
	v_mul_f32_e32 v0, v0, v8
	v_mul_f32_e32 v2, v2, v9
	v_permlane16_swap_b32_e32 v10, v6
	v_permlane16_swap_b32_e32 v11, v7
	v_cvt_pk_bf16_f32 v2, v0, v2
	v_lshlrev_b32_e32 v0, 16, v3
	v_and_b32_e32 v3, 0xffff0000, v3
	v_mul_f32_e32 v0, v0, v10
	v_mul_f32_e32 v3, v3, v11
	v_cvt_pk_bf16_f32 v3, v0, v3
	v_lshlrev_b32_e32 v0, 16, v4
	v_and_b32_e32 v4, 0xffff0000, v4
	v_mul_f32_e32 v0, v0, v12
	v_mul_f32_e32 v4, v4, v13
	v_cvt_pk_bf16_f32 v4, v0, v4
	v_lshlrev_b32_e32 v0, 16, v5
	v_and_b32_e32 v5, 0xffff0000, v5
	v_mul_f32_e32 v5, v5, v7
	v_mul_f32_e32 v0, v0, v6
	v_cvt_pk_bf16_f32 v5, v0, v5
	global_store_dwordx4 v[14:15], v[2:5], off offset:192 sc1
	s_nop 0
	v_readfirstlane_b32 s38, v153
	s_ashr_i32 s38, s38, 6
	s_lshl_b32 s62, s38, 4
	v_and_b32_e32 v2, 15, v153
	s_add_i32 s62, s62, s39
	v_or_b32_e32 v4, s62, v2
	v_ashrrev_i32_e32 v5, 31, v4
	v_lshl_add_u64 v[136:137], s[44:45], 0, v[4:5]
	v_mov_b64_e32 v[4:5], s[28:29]
	v_mad_u64_u32 v[4:5], s[62:63], v136, s23, v[4:5]
	v_mad_i32_i24 v5, v137, s23, v5
	v_lshl_add_u64 v[138:139], v[4:5], 0, s[30:31]
	v_and_b32_e32 v0, 48, v153
	v_lshl_add_u64 v[4:5], v[138:139], 0, v[0:1]
	global_load_dwordx4 v[36:39], v[4:5], off
	global_load_dwordx4 v[40:43], v[4:5], off offset:64
	global_load_dwordx4 v[44:47], v[4:5], off offset:128
	global_load_dwordx4 v[52:55], v[4:5], off offset:192
	s_cmp_lt_i32 s38, 4
	s_cbranch_scc1 .LBB0_419
	s_setprio 0
